# v7 + norm1 row pass with fully coalesced lane-to-column mapping (lane owns 4 groups of 4 columns)
# speedup vs baseline: 1.0002x; 1.0002x over previous
; __global__ void __launch_bounds__(NWAVES * 64, 2) fwd_kernel(Args args_unused) {
;     ...
;         { const int nrow = grouped ? (4 * SEQ + 4 * CTXL) : MT;
;           for (int r = gw; r < nrow; r += NGW) { const int mrow = (!grouped || r < 4 * SEQ) ? r : ML + (r - 4 * SEQ); P1_ROW(mrow); } }
.LBB0_170:
	s_cmp_lt_i32 s89, 2
	s_cselect_b64 s[10:11], -1, 0
	s_and_b64 s[0:1], s[10:11], s[20:21]
	s_andn2_b64 vcc, exec, s[0:1]
	s_cbranch_vccnz .LBB0_183
	v_mbcnt_lo_u32_b32 v128, -1, 0
	v_mbcnt_hi_u32_b32 v128, -1, v128
	s_load_dwordx2 s[12:13], s[96:97], 0xb0
	s_waitcnt lgkmcnt(0)
	s_load_dwordx2 s[4:5], s[96:97], 0
	s_waitcnt lgkmcnt(0)
	s_load_dwordx2 s[6:7], s[96:97], 16
	s_waitcnt lgkmcnt(0)
	s_movk_i32 s3, 0x4400
	s_and_b64 s[0:1], s[18:19], exec
	s_load_dwordx2 s[14:15], s[96:97], 48
	s_waitcnt lgkmcnt(0)
	s_mov_b32 s0, 0x8800
	s_cmp_ge_i32 s22, s0
	s_cbranch_scc1 .LBB0_178
	v_mbcnt_lo_u32_b32 v0, -1, 0
	v_mbcnt_hi_u32_b32 v0, -1, v0
	v_and_b32_e32 v1, 64, v0
	v_add_u32_e32 v1, 64, v1
	v_xor_b32_e32 v2, 1, v0
	v_cmp_lt_i32_e32 vcc, v2, v1
	v_lshlrev_b32_e32 v4, 2, v128
	v_ashrrev_i32_e32 v5, 31, v4
	v_cndmask_b32_e32 v2, v0, v2, vcc
	v_lshlrev_b32_e32 v6, 2, v2
	v_xor_b32_e32 v2, 2, v0
	v_cmp_lt_i32_e32 vcc, v2, v1
	s_mov_b64 s[16:17], 0x2000000
	s_mov_b32 s9, 0
	v_cndmask_b32_e32 v2, v0, v2, vcc
	v_lshlrev_b32_e32 v7, 2, v2
	v_xor_b32_e32 v2, 4, v0
	v_cmp_lt_i32_e32 vcc, v2, v1
	v_mov_b32_e32 v12, 0x358637bd
	s_mov_b32 s1, 0x800000
	v_cndmask_b32_e32 v2, v0, v2, vcc
	v_lshlrev_b32_e32 v8, 2, v2
	v_xor_b32_e32 v2, 8, v0
	v_cmp_lt_i32_e32 vcc, v2, v1
	s_movk_i32 s3, 0x1000
	s_mov_b32 s23, s22
	v_cndmask_b32_e32 v2, v0, v2, vcc
	v_lshlrev_b32_e32 v9, 2, v2
	v_xor_b32_e32 v2, 16, v0
	v_cmp_lt_i32_e32 vcc, v2, v1
	s_nop 1
	v_cndmask_b32_e32 v2, v0, v2, vcc
	v_lshlrev_b32_e32 v10, 2, v2
	v_xor_b32_e32 v2, 32, v0
	v_cmp_lt_i32_e32 vcc, v2, v1
	s_nop 1
	v_cndmask_b32_e32 v0, v0, v2, vcc
	v_lshlrev_b32_e32 v11, 2, v0
	v_lshl_add_u64 v[0:1], v[4:5], 1, s[12:13]
	v_lshl_add_u64 v[0:1], v[0:1], 0, s[16:17]
	v_lshl_add_u64 v[2:3], v[4:5], 2, s[14:15]
	v_lshlrev_b64 v[4:5], 2, v[4:5]
	s_mov_b64 s[14:15], 0x1000
	s_branch .LBB0_174
.LBB0_173:
	v_lshl_add_u64 v[30:31], s[20:21], 0, v[4:5]
	global_load_dwordx4 v[14:17], v[30:31], off
	global_load_dwordx4 v[18:21], v[30:31], off offset:1024
	global_load_dwordx4 v[22:25], v[30:31], off offset:3072
	global_load_dwordx4 v[26:29], v[30:31], off offset:2048
	s_min_i32 s8, s16, 0x8000
	s_ashr_i32 s8, s8, 12
	s_mul_hi_i32 s21, s8, 0x6000
	s_mulk_i32 s8, 0x6000
	s_add_u32 s20, s12, s8
	s_addc_u32 s21, s13, s21
	v_lshl_add_u64 v[54:55], s[20:21], 0, v[4:5]
	v_add_co_u32_e32 v30, vcc, s3, v54
	v_lshl_add_u64 v[56:57], v[54:55], 0, s[14:15]
	s_nop 0
	v_addc_co_u32_e32 v31, vcc, 0, v55, vcc
	global_load_dwordx4 v[30:33], v[30:31], off
	s_nop 0
	global_load_dwordx4 v[34:37], v[56:57], off offset:1024
	global_load_dwordx4 v[38:41], v[2:3], off offset:1024
	global_load_dwordx4 v[42:45], v[2:3], off
	global_load_dwordx4 v[46:49], v[54:55], off offset:1024
	global_load_dwordx4 v[50:53], v[54:55], off
	s_lshl_b64 s[16:17], s[16:17], 11
	s_add_i32 s23, s23, s24
	s_cmp_ge_i32 s23, s0
	s_waitcnt vmcnt(9)
	v_pk_mul_f32 v[58:59], v[16:17], v[16:17]
	v_pk_mul_f32 v[60:61], v[14:15], v[14:15]
	s_waitcnt vmcnt(8)
	v_pk_mul_f32 v[62:63], v[20:21], v[20:21]
	v_pk_mul_f32 v[64:65], v[18:19], v[18:19]
	v_pk_mov_b32 v[70:71], v[60:61], v[58:59] op_sel:[1,0]
	v_mov_b32_e32 v61, v59
	v_pk_mov_b32 v[58:59], v[64:65], v[62:63] op_sel:[1,0]
	v_mov_b32_e32 v65, v63
	s_waitcnt vmcnt(7)
	v_mul_f32_e32 v69, v23, v23
	s_waitcnt vmcnt(6)
	v_mul_f32_e32 v66, v27, v27
	v_mul_f32_e32 v68, v29, v29
	v_pk_add_f32 v[60:61], v[70:71], v[60:61]
	v_pk_add_f32 v[58:59], v[58:59], v[64:65]
	v_mul_f32_e32 v13, v22, v22
	v_mul_f32_e32 v72, v24, v24
	v_mul_f32_e32 v73, v25, v25
	v_pk_fma_f32 v[62:63], v[26:27], v[26:27], v[66:67] op_sel_hi:[1,1,0]
	v_pk_fma_f32 v[66:67], v[28:29], v[28:29], v[68:69] op_sel_hi:[1,1,0]
	v_pk_add_f32 v[60:61], v[60:61], v[60:61] op_sel:[0,1] op_sel_hi:[1,0]
	v_pk_add_f32 v[58:59], v[58:59], v[58:59] op_sel:[0,1] op_sel_hi:[1,0]
	v_mov_b32_e32 v63, v72
	v_mov_b32_e32 v67, v73
	v_mov_b32_e32 v61, v13
	v_mov_b32_e32 v59, v69
	v_pk_add_f32 v[62:63], v[62:63], v[66:67]
	v_pk_add_f32 v[58:59], v[60:61], v[58:59]
	s_waitcnt vmcnt(5)
	v_pk_add_f32 v[32:33], v[32:33], 1.0 op_sel_hi:[1,0]
	v_pk_add_f32 v[58:59], v[58:59], v[62:63]
	v_pk_add_f32 v[30:31], v[30:31], 1.0 op_sel_hi:[1,0]
	v_add_f32_e32 v13, v58, v59
	ds_bpermute_b32 v58, v6, v13
	s_waitcnt vmcnt(4)
	v_pk_add_f32 v[36:37], v[36:37], 1.0 op_sel_hi:[1,0]
	v_pk_add_f32 v[34:35], v[34:35], 1.0 op_sel_hi:[1,0]
	s_waitcnt lgkmcnt(0)
	v_add_f32_e32 v13, v13, v58
	ds_bpermute_b32 v58, v7, v13
	s_waitcnt lgkmcnt(0)
	v_add_f32_e32 v13, v13, v58
	ds_bpermute_b32 v58, v8, v13
	s_waitcnt lgkmcnt(0)
	v_add_f32_e32 v13, v13, v58
	ds_bpermute_b32 v58, v9, v13
	s_waitcnt lgkmcnt(0)
	v_add_f32_e32 v13, v13, v58
	ds_bpermute_b32 v58, v10, v13
	s_waitcnt lgkmcnt(0)
	v_add_f32_e32 v13, v13, v58
	ds_bpermute_b32 v60, v11, v13
	v_lshl_add_u64 v[58:59], v[0:1], 0, s[16:17]
	s_waitcnt lgkmcnt(0)
	v_add_f32_e32 v13, v13, v60
	v_fmamk_f32 v13, v13, 0x3a800000, v12
	v_mul_f32_e32 v60, 0x4b800000, v13
	v_cmp_gt_f32_e32 vcc, s1, v13
	s_nop 1
	v_cndmask_b32_e32 v13, v13, v60, vcc
	v_rsq_f32_e32 v13, v13
	s_nop 0
	v_mul_f32_e32 v60, 0x45800000, v13
	v_cndmask_b32_e32 v60, v13, v60, vcc
	v_pk_mul_f32 v[16:17], v[60:61], v[16:17] op_sel_hi:[0,1]
	v_pk_mul_f32 v[14:15], v[60:61], v[14:15] op_sel_hi:[0,1]
	v_pk_mul_f32 v[20:21], v[60:61], v[20:21] op_sel_hi:[0,1]
	v_pk_mul_f32 v[18:19], v[60:61], v[18:19] op_sel_hi:[0,1]
	s_waitcnt vmcnt(2)
	v_pk_mul_f32 v[14:15], v[42:43], v[14:15]
	v_pk_mul_f32 v[16:17], v[44:45], v[16:17]
	v_pk_mul_f32 v[18:19], v[38:39], v[18:19]
	v_pk_mul_f32 v[20:21], v[40:41], v[20:21]
	s_waitcnt vmcnt(0)
	v_pk_fma_f32 v[16:17], v[32:33], v[16:17], v[52:53]
	v_pk_fma_f32 v[14:15], v[30:31], v[14:15], v[50:51]
	v_pk_fma_f32 v[20:21], v[36:37], v[20:21], v[48:49]
	v_pk_fma_f32 v[18:19], v[34:35], v[18:19], v[46:47]
	v_cvt_pk_bf16_f32 v14, v14, v15
	v_cvt_pk_bf16_f32 v15, v16, v17
	v_cvt_pk_bf16_f32 v16, v18, v19
	v_cvt_pk_bf16_f32 v17, v20, v21
	global_store_dwordx2 v[58:59], v[14:15], off
	global_store_dwordx2 v[58:59], v[16:17], off offset:512
	global_load_dwordx4 v[14:17], v[56:57], off offset:2048
	s_nop 0
	global_load_dwordx4 v[18:21], v[2:3], off offset:2048
	global_load_dwordx4 v[30:33], v[56:57], off offset:3072
	global_load_dwordx4 v[34:37], v[2:3], off offset:3072
	global_load_dwordx4 v[38:41], v[54:55], off offset:2048
	global_load_dwordx4 v[42:45], v[54:55], off offset:3072
	v_pk_mul_f32 v[28:29], v[60:61], v[28:29] op_sel_hi:[0,1]
	v_pk_mul_f32 v[26:27], v[60:61], v[26:27] op_sel_hi:[0,1]
	v_pk_mul_f32 v[24:25], v[60:61], v[24:25] op_sel_hi:[0,1]
	v_pk_mul_f32 v[22:23], v[60:61], v[22:23] op_sel_hi:[0,1]
	s_waitcnt vmcnt(5)
	v_pk_add_f32 v[16:17], v[16:17], 1.0 op_sel_hi:[1,0]
	v_pk_add_f32 v[14:15], v[14:15], 1.0 op_sel_hi:[1,0]
	s_waitcnt vmcnt(4)
	v_pk_mul_f32 v[18:19], v[18:19], v[26:27]
	v_pk_mul_f32 v[20:21], v[20:21], v[28:29]
	s_waitcnt vmcnt(3)
	v_pk_add_f32 v[26:27], v[32:33], 1.0 op_sel_hi:[1,0]
	v_pk_add_f32 v[28:29], v[30:31], 1.0 op_sel_hi:[1,0]
	s_waitcnt vmcnt(2)
	v_pk_mul_f32 v[22:23], v[34:35], v[22:23]
	v_pk_mul_f32 v[24:25], v[36:37], v[24:25]
	s_waitcnt vmcnt(1)
	v_pk_fma_f32 v[16:17], v[16:17], v[20:21], v[40:41]
	v_pk_fma_f32 v[14:15], v[14:15], v[18:19], v[38:39]
	s_waitcnt vmcnt(0)
	v_pk_fma_f32 v[18:19], v[26:27], v[24:25], v[44:45]
	v_pk_fma_f32 v[20:21], v[28:29], v[22:23], v[42:43]
	v_cvt_pk_bf16_f32 v14, v14, v15
	v_cvt_pk_bf16_f32 v15, v16, v17
	v_cvt_pk_bf16_f32 v16, v20, v21
	v_cvt_pk_bf16_f32 v17, v18, v19
	global_store_dwordx2 v[58:59], v[14:15], off offset:1024
	global_store_dwordx2 v[58:59], v[16:17], off offset:1536
	s_cbranch_scc1 .LBB0_178
